# input-projection epilogue: counted vmcnt(1) instead of full drain after each store (loads already complete on every path)
# speedup vs baseline: 1.0298x; 1.0116x over previous
; DEV void phase_gemm(const Params& p, int l, int mode) {
;     ...
; #pragma unroll
;           for (int q = 0; q < 8; ++q) {
;               const int ai = q >> 2, m = q & 3;
;               ROPE_LOAD(q);
.LBB0_370:
	s_waitcnt vmcnt(1)
	v_mov_b32_e32 v136, v128
	v_mov_b32_e32 v137, v129
	v_mov_b32_e32 v138, v130
	v_mov_b32_e32 v139, v131
	s_branch .LBB0_383

; DEV void phase_gemm(const Params& p, int l, int mode) {
;     ...
;               if (ropeR) {
; #pragma unroll
;                 for (int n = 0; n < 2; ++n)
; #pragma unroll
;                   for (int h2 = 0; h2 < 2; ++h2) {
;                     const f32x4 cs = tb[0][n * 2 + h2];
;                     float x1 = acc[ai][0][m][n][2 * h2], x2 = acc[ai][1][m][n][2 * h2];
;                     acc[ai][0][m][n][2 * h2] = x1 * cs[0] - x2 * cs[1]; acc[ai][1][m][n][2 * h2] = x1 * cs[1] + x2 * cs[0];
;                     x1 = acc[ai][0][m][n][2 * h2 + 1]; x2 = acc[ai][1][m][n][2 * h2 + 1];
;                     acc[ai][0][m][n][2 * h2 + 1] = x1 * cs[2] - x2 * cs[3]; acc[ai][1][m][n][2 * h2 + 1] = x1 * cs[3] + x2 * cs[2];
;                   }
;               }
.LBB0_382:
	s_waitcnt vmcnt(1)
	v_mov_b32_e32 v17, v138
	v_mov_b32_e32 v138, v137
	v_pk_mul_f32 v[18:19], v[138:139], v[150:151]
	v_pk_mul_f32 v[140:141], v[138:139], v[128:129]
	v_mul_f32_e32 v138, v132, v130
	v_mul_f32_e32 v142, v133, v148
	v_mul_f32_e32 v132, v132, v148
	v_mov_b32_e32 v148, v131
	v_mov_b32_e32 v16, v136
	v_mul_f32_e32 v144, v133, v130
	v_pk_mul_f32 v[136:137], v[134:135], v[148:149]
	v_mov_b32_e32 v130, v149
	v_mov_b32_e32 v139, v136
	v_mov_b32_e32 v143, v137
	v_pk_fma_f32 v[136:137], v[16:17], v[128:129], v[18:19] neg_lo:[0,0,1] neg_hi:[0,0,1]
	v_pk_mul_f32 v[18:19], v[134:135], v[130:131]
	v_pk_add_f32 v[138:139], v[138:139], v[142:143] neg_lo:[0,1] neg_hi:[0,1]
	v_mov_b32_e32 v133, v18
	v_mov_b32_e32 v145, v19
	v_mov_b64_e32 v[128:129], v[136:137]
	v_pk_fma_f32 v[150:151], v[16:17], v[150:151], v[140:141]
	v_pk_add_f32 v[148:149], v[132:133], v[144:145]
	v_mov_b64_e32 v[130:131], v[138:139]

; DEV void phase_gemm(const Params& p, int l, int mode) {
;     ...
; #pragma unroll
;           for (int q = 0; q < 8; ++q) {
;               const int ai = q >> 2, m = q & 3;
;               ROPE_LOAD(q);
.LBB0_436:
	s_waitcnt vmcnt(1)
	v_mov_b32_e32 v136, v128
	v_mov_b32_e32 v137, v129
	v_mov_b32_e32 v138, v130
	v_mov_b32_e32 v139, v131
	s_and_b64 vcc, exec, s[26:27]
	s_mov_b64 s[0:1], -1
	s_cbranch_vccnz .LBB0_469
	s_branch .LBB0_449

; DEV void phase_gemm(const Params& p, int l, int mode) {
;     ...
;               if (ropeR) {
; #pragma unroll
;                 for (int n = 0; n < 2; ++n)
; #pragma unroll
;                   for (int h2 = 0; h2 < 2; ++h2) {
;                     const f32x4 cs = tb[0][n * 2 + h2];
;                     float x1 = acc[ai][0][m][n][2 * h2], x2 = acc[ai][1][m][n][2 * h2];
;                     acc[ai][0][m][n][2 * h2] = x1 * cs[0] - x2 * cs[1]; acc[ai][1][m][n][2 * h2] = x1 * cs[1] + x2 * cs[0];
;                     x1 = acc[ai][0][m][n][2 * h2 + 1]; x2 = acc[ai][1][m][n][2 * h2 + 1];
;                     acc[ai][0][m][n][2 * h2 + 1] = x1 * cs[2] - x2 * cs[3]; acc[ai][1][m][n][2 * h2 + 1] = x1 * cs[3] + x2 * cs[2];
;                   }
;               }
.LBB0_448:
	s_waitcnt vmcnt(1)
	v_mov_b32_e32 v17, v138
	v_mov_b32_e32 v138, v137
	v_pk_mul_f32 v[18:19], v[138:139], v[150:151]
	v_pk_mul_f32 v[140:141], v[138:139], v[128:129]
	v_mul_f32_e32 v138, v132, v130
	v_mul_f32_e32 v142, v133, v148
	v_mul_f32_e32 v132, v132, v148
	v_mov_b32_e32 v148, v131
	v_mov_b32_e32 v16, v136
	v_mul_f32_e32 v144, v133, v130
	v_pk_mul_f32 v[136:137], v[134:135], v[148:149]
	v_mov_b32_e32 v130, v149
	v_mov_b32_e32 v139, v136
	v_mov_b32_e32 v143, v137
	v_pk_fma_f32 v[136:137], v[16:17], v[128:129], v[18:19] neg_lo:[0,0,1] neg_hi:[0,0,1]
	v_pk_mul_f32 v[18:19], v[134:135], v[130:131]
	v_pk_add_f32 v[138:139], v[138:139], v[142:143] neg_lo:[0,1] neg_hi:[0,1]
	v_mov_b32_e32 v133, v18
	v_mov_b32_e32 v145, v19
	v_mov_b64_e32 v[128:129], v[136:137]
	v_pk_fma_f32 v[150:151], v[16:17], v[150:151], v[140:141]
	v_pk_add_f32 v[148:149], v[132:133], v[144:145]
	v_mov_b64_e32 v[130:131], v[138:139]
	s_and_b64 vcc, exec, s[26:27]
	s_mov_b64 s[0:1], -1
	s_cbranch_vccnz .LBB0_469

; DEV void phase_gemm(const Params& p, int l, int mode) {
;     ...
; #pragma unroll
;           for (int q = 0; q < 8; ++q) {
;               const int ai = q >> 2, m = q & 3;
;               ROPE_LOAD(q);
.LBB0_631:
	s_waitcnt vmcnt(1)
	v_mov_b32_e32 v136, v128
	v_mov_b32_e32 v137, v129
	v_mov_b32_e32 v138, v130
	v_mov_b32_e32 v139, v131
	s_and_b64 vcc, exec, s[26:27]
	s_mov_b64 s[0:1], -1
	s_cbranch_vccz .LBB0_654
